# s15 + attention: movs / p1 log2 fma / l updates run between the last P.V MFMA and the tile barrier instead of after it (RESC temporaries renamed)
# speedup vs baseline: 1.0039x; 1.0039x over previous
; __device__ __forceinline__ void finishSM(f32x16& p0, f32x16& p1, float alpha, float& l_reg, bf16x8& pa0, bf16x8& pa1, bf16x8& pa2, bf16x8& pa3) {
;   for (int r = 0; r < 16; ++r) p1[r] = __builtin_amdgcn_exp2f(p1[r]);
;   float ps = 0; for (int r = 0; r < 16; ++r) ps += p0[r]; for (int r = 0; r < 16; ++r) ps += p1[r];
;   { auto rr = __builtin_amdgcn_permlane32_swap(__float_as_uint(ps), __float_as_uint(ps), false, false);
;     ps = __uint_as_float(rr[0]) + __uint_as_float(rr[1]); }
;   l_reg = l_reg * alpha + ps;
;     ...
;   PK4(p0, 0, pa0); PK4(p0, 8, pa1); PK4(p1, 0, pa2); PK4(p1, 8, pa3);
;     ...
; }
; __device__ __forceinline__ void qkt(f32x16& p0, f32x16& p1, const bf16* Ks, const bf16x8* qr, int r32, int hi) {
;   p0 = f32x16{}; p1 = f32x16{};
;   for (int d0 = 0; d0 < 8; ++d0) { int cb = (d0 * 16 + hi * 8) * 2;
;     bf16x8 b0 = *reinterpret_cast<const bf16x8*>((const char*)Ks + KSWZ(r32, cb));
;     bf16x8 b1 = *reinterpret_cast<const bf16x8*>((const char*)Ks + KSWZ(32 + r32, cb));
;     p0 = __builtin_amdgcn_mfma_f32_32x32x16_bf16(b0, qr[d0], p0, 0, 0, 0);
;     p1 = __builtin_amdgcn_mfma_f32_32x32x16_bf16(b1, qr[d0], p1, 0, 0, 0); }
.LBB0_602:
	ds_read_b128 v[64:67], v192 offset:49152
	ds_read_b128 v[68:71], v192 offset:57344
	ds_read_b128 v[242:245], v201 offset:49152
	ds_read_b128 v[246:249], v201 offset:57344
	v_exp_f32_e32 v160, v162
	v_add_f32_e32 v162, 0, v223
	s_waitcnt lgkmcnt(3)
	v_mfma_f32_32x32x16_bf16 v[80:95], v[64:67], v[126:129], 0
	v_add_f32_e32 v162, v224, v162
	v_add_f32_e32 v162, v225, v162
	v_add_f32_e32 v162, v227, v162
	v_add_f32_e32 v162, v229, v162
	v_add_f32_e32 v162, v230, v162
	v_add_f32_e32 v162, v226, v162
	v_add_f32_e32 v162, v228, v162
	s_waitcnt lgkmcnt(2)
	v_mfma_f32_32x32x16_bf16 v[64:79], v[68:71], v[126:129], 0
	v_add_f32_e32 v162, v215, v162
	v_add_f32_e32 v162, v217, v162
	v_add_f32_e32 v162, v219, v162
	v_add_f32_e32 v162, v221, v162
	v_add_f32_e32 v162, v216, v162
	v_add_f32_e32 v162, v218, v162
	v_add_f32_e32 v162, v220, v162
	s_waitcnt lgkmcnt(1)
	v_mfma_f32_32x32x16_bf16 v[80:95], v[242:245], v[122:125], v[80:95]
	v_add_f32_e32 v162, v222, v162
	v_exp_f32_e32 v154, v164
	v_exp_f32_e32 v155, v165
	v_exp_f32_e32 v156, v172
	v_exp_f32_e32 v157, v173
	v_exp_f32_e32 v158, v168
	v_exp_f32_e32 v159, v169
	s_waitcnt lgkmcnt(0)
	v_mfma_f32_32x32x16_bf16 v[64:79], v[246:249], v[122:125], v[64:79]
	ds_read_b128 v[242:245], v200 offset:49152
	ds_read_b128 v[246:249], v200 offset:57344
	v_exp_f32_e32 v161, v163
	v_cvt_pk_bf16_f32 v164, v229, v230
	v_cvt_pk_bf16_f32 v163, v225, v227
	v_cvt_pk_bf16_f32 v165, v226, v228
	v_cvt_pk_bf16_f32 v168, v216, v218
	v_cvt_pk_bf16_f32 v169, v220, v222
	s_waitcnt lgkmcnt(1)
	v_mfma_f32_32x32x16_bf16 v[80:95], v[242:245], v[134:137], v[80:95]
	v_exp_f32_e32 v146, v176
	v_exp_f32_e32 v147, v177
	v_exp_f32_e32 v148, v174
	v_exp_f32_e32 v149, v175
	v_permlane32_swap_b32_e32 v163, v165
	s_waitcnt lgkmcnt(0)
	v_mfma_f32_32x32x16_bf16 v[64:79], v[246:249], v[134:137], v[64:79]
	ds_read_b128 v[242:245], v195 offset:49152
	ds_read_b128 v[246:249], v195 offset:57344
	v_add_f32_e32 v162, v146, v162
	v_add_f32_e32 v162, v147, v162
	v_add_f32_e32 v162, v148, v162
	v_exp_f32_e32 v150, v170
	s_waitcnt lgkmcnt(1)
	v_mfma_f32_32x32x16_bf16 v[80:95], v[242:245], v[130:133], v[80:95]
	v_exp_f32_e32 v151, v171
	v_exp_f32_e32 v152, v166
	v_exp_f32_e32 v153, v167
	v_add_f32_e32 v162, v149, v162
	s_waitcnt lgkmcnt(0)
	v_mfma_f32_32x32x16_bf16 v[64:79], v[246:249], v[130:133], v[64:79]
	ds_read_b128 v[242:245], v194 offset:49152
	ds_read_b128 v[246:249], v194 offset:57344
	v_add_f32_e32 v162, v150, v162
	v_add_f32_e32 v162, v151, v162
	v_add_f32_e32 v162, v152, v162
	v_add_f32_e32 v162, v153, v162
	s_waitcnt lgkmcnt(1)
	v_mfma_f32_32x32x16_bf16 v[80:95], v[242:245], v[118:121], v[80:95]
	v_add_f32_e32 v162, v154, v162
	v_add_f32_e32 v162, v155, v162
	v_add_f32_e32 v162, v156, v162
	v_add_f32_e32 v162, v157, v162
	s_waitcnt lgkmcnt(0)
	v_mfma_f32_32x32x16_bf16 v[64:79], v[246:249], v[118:121], v[64:79]
	ds_read_b128 v[242:245], v193 offset:49152
	ds_read_b128 v[246:249], v193 offset:57344
	v_add_f32_e32 v162, v158, v162
	v_add_f32_e32 v162, v159, v162
	v_add_f32_e32 v162, v160, v162
	v_add_f32_e32 v211, v161, v162
	s_waitcnt lgkmcnt(1)
	v_mfma_f32_32x32x16_bf16 v[80:95], v[242:245], v[114:117], v[80:95]
	v_mov_b32_e32 v212, v211
	v_cvt_pk_bf16_f32 v162, v223, v224
	s_nop 0
	v_permlane32_swap_b32_e32 v211, v212
	s_waitcnt lgkmcnt(0)
	v_mfma_f32_32x32x16_bf16 v[64:79], v[246:249], v[114:117], v[64:79]
	ds_read_b128 v[242:245], v207 offset:49152
	ds_read_b128 v[246:249], v207 offset:57344
	v_permlane32_swap_b32_e32 v162, v164
	v_cvt_pk_bf16_f32 v166, v215, v217
	v_cvt_pk_bf16_f32 v167, v219, v221
	v_cvt_pk_bf16_f32 v170, v146, v147
	s_waitcnt lgkmcnt(1)
	v_mfma_f32_32x32x16_bf16 v[80:95], v[242:245], v[110:113], v[80:95]
	v_cvt_pk_bf16_f32 v171, v148, v149
	v_cvt_pk_bf16_f32 v172, v150, v151
	v_cvt_pk_bf16_f32 v173, v152, v153
	v_cvt_pk_bf16_f32 v174, v154, v155
	s_waitcnt lgkmcnt(0)
	v_mfma_f32_32x32x16_bf16 v[64:79], v[246:249], v[110:113], v[64:79]
	ds_read_b128 v[242:245], v206 offset:49152
	ds_read_b128 v[246:249], v206 offset:57344
	v_cvt_pk_bf16_f32 v175, v156, v157
	v_cvt_pk_bf16_f32 v176, v158, v159
	v_cvt_pk_bf16_f32 v177, v160, v161
	s_waitcnt lgkmcnt(1)
	v_mfma_f32_32x32x16_bf16 v[80:95], v[242:245], v[106:109], v[80:95]
	v_permlane32_swap_b32_e32 v166, v168
	v_permlane32_swap_b32_e32 v167, v169
	v_permlane32_swap_b32_e32 v170, v172
	s_waitcnt lgkmcnt(0)
	v_mfma_f32_32x32x16_bf16 v[64:79], v[246:249], v[106:109], v[64:79]
	v_permlane32_swap_b32_e32 v171, v173
	v_permlane32_swap_b32_e32 v174, v176
	v_permlane32_swap_b32_e32 v175, v177
	v_add_co_u32_e32 v146, vcc, s69, v182
	s_mov_b32 s8, 0xffff0000
	s_nop 0
	v_addc_co_u32_e32 v147, vcc, -1, v183, vcc
	v_add_co_u32_e32 v150, vcc, s8, v182
	s_mov_b32 s8, 0xff6e8000
	s_nop 0
	v_addc_co_u32_e32 v151, vcc, -1, v183, vcc
	v_add_co_u32_e32 v154, vcc, s8, v182
	s_mov_b32 s8, 0xff6f0000
	s_nop 0
	v_addc_co_u32_e32 v155, vcc, -1, v183, vcc
	v_add_co_u32_e32 v158, vcc, s8, v182
	global_load_dwordx4 v[146:149], v[146:147], off
	s_nop 0
	global_load_dwordx4 v[150:153], v[150:151], off
	v_addc_co_u32_e32 v159, vcc, -1, v183, vcc
	global_load_dwordx4 v[154:157], v[154:155], off
	s_nop 0
	global_load_dwordx4 v[158:161], v[158:159], off
	ds_read_b64_tr_b16 v[214:215], v179 offset:0
	ds_read_b64_tr_b16 v[216:217], v179 offset:0x800
	ds_read_b64_tr_b16 v[218:219], v179 offset:0x1000
	ds_read_b64_tr_b16 v[220:221], v179 offset:0x1800
	ds_read_b64_tr_b16 v[222:223], v179 offset:0x2000
	ds_read_b64_tr_b16 v[224:225], v179 offset:0x2800
	ds_read_b64_tr_b16 v[226:227], v179 offset:0x3000
	ds_read_b64_tr_b16 v[228:229], v179 offset:0x3800
	s_waitcnt vmcnt(4)
; #define SBAR() __builtin_amdgcn_sched_barrier(0)
; __device__ __forceinline__ void partialSM(f32x16& p0, f32x16& p1, float& m_reg, float& mn, float& alpha) {
;   constexpr float C = SCALE * 1.4426950408889634f;
;   float pmax = p0[0]; for (int r = 1; r < 16; ++r) pmax = fmaxf(pmax, p0[r]); for (int r = 0; r < 16; ++r) pmax = fmaxf(pmax, p1[r]);
;   { auto rr = __builtin_amdgcn_permlane32_swap(__float_as_uint(pmax), __float_as_uint(pmax), false, false);
;     pmax = fmaxf(__uint_as_float(rr[0]), __uint_as_float(rr[1])); }
;   if (__builtin_expect(__all(pmax - m_reg <= THR / SCALE), 1)) { mn = m_reg; alpha = 1.f; }
;   else { mn = fmaxf(m_reg, pmax); alpha = __builtin_amdgcn_exp2f((m_reg - mn) * C); m_reg = mn; }
;   float mnC = -mn * C;
;   for (int r = 0; r < 16; ++r) p0[r] = fmaf(p0[r], C, mnC); for (int r = 0; r < 16; ++r) p1[r] = fmaf(p1[r], C, mnC);
;   for (int r = 0; r < 16; ++r) p0[r] = __builtin_amdgcn_exp2f(p0[r]);
; }
; template <int D0> __device__ __forceinline__ void pv_one(f32x16& od, int vb, bf16x8 pa0, bf16x8 pa1, bf16x8 pa2, bf16x8 pa3) {
;   const s16x4 l0 = tr_read<v_rd_off(D0, 0, 0)>(vb), h0 = tr_read<v_rd_off(D0, 0, 1)>(vb), l1 = tr_read<v_rd_off(D0, 1, 0)>(vb), h1 = tr_read<v_rd_off(D0, 1, 1)>(vb);
;   const s16x4 l2 = tr_read<v_rd_off(D0, 2, 0)>(vb), h2 = tr_read<v_rd_off(D0, 2, 1)>(vb), l3 = tr_read<v_rd_off(D0, 3, 0)>(vb), h3 = tr_read<v_rd_off(D0, 3, 1)>(vb);
;   asm volatile("s_waitcnt lgkmcnt(0)" ::: "memory"); SBAR();
;     ...
;   od = __builtin_amdgcn_mfma_f32_32x32x16_bf16(pa0, PK(l0, h0), od, 0, 0, 0);
;   od = __builtin_amdgcn_mfma_f32_32x32x16_bf16(pa1, PK(l1, h1), od, 0, 0, 0);
;   od = __builtin_amdgcn_mfma_f32_32x32x16_bf16(pa2, PK(l2, h2), od, 0, 0, 0);
;   od = __builtin_amdgcn_mfma_f32_32x32x16_bf16(pa3, PK(l3, h3), od, 0, 0, 0);
;     ...
; }
; __device__ __forceinline__ void pv_d0(f32x16* o, int vb, bf16x8 pa0, bf16x8 pa1, bf16x8 pa2, bf16x8 pa3) {
;   pv_one<0>(o[0], vb, pa0, pa1, pa2, pa3); pv_one<1>(o[1], vb, pa0, pa1, pa2, pa3); pv_one<2>(o[2], vb, pa0, pa1, pa2, pa3); pv_one<3>(o[3], vb, pa0, pa1, pa2, pa3);
	ds_write_b128 v202, v[102:105] offset:32768
	ds_write_b128 v203, v[142:145] offset:32768
	s_waitcnt lgkmcnt(2)
	s_nop 0
	v_mfma_f32_32x32x16_bf16 v[0:15], v[162:165], v[214:217], v[0:15]
	ds_read_b64_tr_b16 v[214:215], v179 offset:0x200
	ds_read_b64_tr_b16 v[216:217], v179 offset:0xa00
	v_max_f32_e32 v232, v81, v81
	v_max_f32_e32 v233, v80, v80
	v_max_f32_e32 v232, v233, v232
	v_max3_f32 v232, v232, v82, v83
	v_max3_f32 v232, v232, v84, v85
	v_max3_f32 v232, v232, v86, v87
	v_mfma_f32_32x32x16_bf16 v[0:15], v[166:169], v[218:221], v[0:15]
	ds_read_b64_tr_b16 v[218:219], v179 offset:0x1200
	ds_read_b64_tr_b16 v[220:221], v179 offset:0x1a00
	v_max3_f32 v232, v232, v88, v89
	v_max3_f32 v232, v232, v90, v91
	v_max3_f32 v232, v232, v92, v93
	v_max3_f32 v232, v232, v94, v95
	v_max3_f32 v232, v232, v64, v65
	v_max3_f32 v232, v232, v66, v67
	v_mfma_f32_32x32x16_bf16 v[0:15], v[170:173], v[222:225], v[0:15]
	ds_read_b64_tr_b16 v[222:223], v179 offset:0x2200
	ds_read_b64_tr_b16 v[224:225], v179 offset:0x2a00
	v_max3_f32 v232, v232, v68, v69
	v_max3_f32 v232, v232, v70, v71
	v_max3_f32 v232, v232, v72, v73
	v_max3_f32 v232, v232, v74, v75
	v_max3_f32 v232, v232, v76, v77
	v_max3_f32 v232, v232, v78, v79
	v_mfma_f32_32x32x16_bf16 v[0:15], v[174:177], v[226:229], v[0:15]
	ds_read_b64_tr_b16 v[226:227], v179 offset:0x3200
	ds_read_b64_tr_b16 v[228:229], v179 offset:0x3a00
	v_mov_b32_e32 v233, v232
	s_nop 1
	v_permlane32_swap_b32_e32 v232, v233
	v_max_f32_e32 v233, v233, v233
	v_max_f32_e32 v232, v232, v232
	v_max_f32_e32 v232, v232, v233
	s_waitcnt lgkmcnt(0)
	v_mfma_f32_32x32x16_bf16 v[48:63], v[162:165], v[214:217], v[48:63]
	ds_read_b64_tr_b16 v[214:215], v179 offset:0x400
	ds_read_b64_tr_b16 v[216:217], v179 offset:0xc00
	v_sub_f32_e32 v233, v232, v210
	v_cmp_ge_f32_e32 vcc, s68, v233
	v_max_f32_e32 v233, v210, v210
	v_max_f32_e32 v232, v233, v232
	v_sub_f32_e32 v233, v210, v232
	v_mul_f32_e32 v233, 0x3e0293ee, v233
	v_mfma_f32_32x32x16_bf16 v[48:63], v[166:169], v[218:221], v[48:63]
	ds_read_b64_tr_b16 v[218:219], v179 offset:0x1400
	ds_read_b64_tr_b16 v[220:221], v179 offset:0x1c00
	s_cmp_eq_u64 vcc, exec
	s_cselect_b64 s[8:9], -1, 0
	v_exp_f32_e32 v233, v233
	v_mfma_f32_32x32x16_bf16 v[48:63], v[170:173], v[222:225], v[48:63]
	ds_read_b64_tr_b16 v[222:223], v179 offset:0x2400
	ds_read_b64_tr_b16 v[224:225], v179 offset:0x2c00
	v_cndmask_b32_e64 v210, v232, v210, s[8:9]
	v_mul_f32_e32 v213, 0xbe0293ee, v210
	v_fmamk_f32 v80, v80, 0x3e0293ee, v213
	v_fmamk_f32 v81, v81, 0x3e0293ee, v213
	v_fmamk_f32 v82, v82, 0x3e0293ee, v213
	v_fmamk_f32 v83, v83, 0x3e0293ee, v213
	v_mfma_f32_32x32x16_bf16 v[48:63], v[174:177], v[226:229], v[48:63]
	ds_read_b64_tr_b16 v[226:227], v179 offset:0x3400
	ds_read_b64_tr_b16 v[228:229], v179 offset:0x3c00
	v_fmamk_f32 v84, v84, 0x3e0293ee, v213
	v_fmamk_f32 v85, v85, 0x3e0293ee, v213
	v_fmamk_f32 v86, v86, 0x3e0293ee, v213
	v_fmamk_f32 v87, v87, 0x3e0293ee, v213
	v_fmamk_f32 v88, v88, 0x3e0293ee, v213
	v_fmamk_f32 v89, v89, 0x3e0293ee, v213
	s_waitcnt lgkmcnt(0)
	v_mfma_f32_32x32x16_bf16 v[32:47], v[162:165], v[214:217], v[32:47]
	ds_read_b64_tr_b16 v[214:215], v179 offset:0x600
	ds_read_b64_tr_b16 v[216:217], v179 offset:0xe00
	v_fmamk_f32 v90, v90, 0x3e0293ee, v213
	v_fmamk_f32 v91, v91, 0x3e0293ee, v213
	v_fmamk_f32 v92, v92, 0x3e0293ee, v213
	v_fmamk_f32 v93, v93, 0x3e0293ee, v213
	v_fmamk_f32 v94, v94, 0x3e0293ee, v213
	v_fmamk_f32 v95, v95, 0x3e0293ee, v213
	v_mfma_f32_32x32x16_bf16 v[32:47], v[166:169], v[218:221], v[32:47]
	ds_read_b64_tr_b16 v[218:219], v179 offset:0x1600
	ds_read_b64_tr_b16 v[220:221], v179 offset:0x1e00
	v_exp_f32_e32 v80, v80
	v_exp_f32_e32 v81, v81
	v_exp_f32_e32 v82, v82
	v_mfma_f32_32x32x16_bf16 v[32:47], v[170:173], v[222:225], v[32:47]
	ds_read_b64_tr_b16 v[222:223], v179 offset:0x2600
	ds_read_b64_tr_b16 v[224:225], v179 offset:0x2e00
	v_exp_f32_e32 v83, v83
	v_exp_f32_e32 v84, v84
	v_exp_f32_e32 v85, v85
	v_mfma_f32_32x32x16_bf16 v[32:47], v[174:177], v[226:229], v[32:47]
	ds_read_b64_tr_b16 v[226:227], v179 offset:0x3600
	ds_read_b64_tr_b16 v[228:229], v179 offset:0x3e00
	v_exp_f32_e32 v86, v86
	v_exp_f32_e32 v87, v87
	v_exp_f32_e32 v88, v88
	s_waitcnt lgkmcnt(0)
	v_mfma_f32_32x32x16_bf16 v[16:31], v[162:165], v[214:217], v[16:31]
	v_exp_f32_e32 v89, v89
	v_exp_f32_e32 v90, v90
	v_exp_f32_e32 v91, v91
	v_mfma_f32_32x32x16_bf16 v[16:31], v[166:169], v[218:221], v[16:31]
	v_exp_f32_e32 v92, v92
	v_exp_f32_e32 v93, v93
	v_mfma_f32_32x32x16_bf16 v[16:31], v[170:173], v[222:225], v[16:31]
	v_exp_f32_e32 v94, v94
	v_exp_f32_e32 v95, v95
	v_mfma_f32_32x32x16_bf16 v[16:31], v[174:177], v[226:229], v[16:31]
	v_mov_b32_e32 v162, v80
	v_mov_b32_e32 v163, v81
	v_mov_b32_e32 v164, v82
	v_mov_b32_e32 v175, v83
	v_mov_b32_e32 v176, v84
	v_mov_b32_e32 v177, v85
	v_mov_b32_e32 v165, v86
	v_mov_b32_e32 v174, v87
	v_mov_b32_e32 v166, v88
	v_mov_b32_e32 v167, v89
	v_mov_b32_e32 v172, v90
	v_mov_b32_e32 v173, v91
	v_mov_b32_e32 v168, v92
	v_mov_b32_e32 v169, v93
	v_mov_b32_e32 v170, v94
	v_mov_b32_e32 v171, v95
	v_fmamk_f32 v223, v64, 0x3e0293ee, v213
	v_fmamk_f32 v224, v65, 0x3e0293ee, v213
	v_fmamk_f32 v225, v66, 0x3e0293ee, v213
	v_fmamk_f32 v226, v67, 0x3e0293ee, v213
	v_fmamk_f32 v227, v68, 0x3e0293ee, v213
	v_fmamk_f32 v216, v69, 0x3e0293ee, v213
	v_fmamk_f32 v217, v70, 0x3e0293ee, v213
	v_fmamk_f32 v218, v71, 0x3e0293ee, v213
	v_fmamk_f32 v219, v72, 0x3e0293ee, v213
	v_fmamk_f32 v220, v73, 0x3e0293ee, v213
	v_fmamk_f32 v221, v74, 0x3e0293ee, v213
	v_fmamk_f32 v222, v75, 0x3e0293ee, v213
	v_fmamk_f32 v215, v76, 0x3e0293ee, v213
	v_fmamk_f32 v228, v77, 0x3e0293ee, v213
	v_fmamk_f32 v229, v78, 0x3e0293ee, v213
	v_fmac_f32_e32 v213, 0x3e0293ee, v79
	s_barrier
	s_waitcnt vmcnt(4)
	v_cndmask_b32_e64 v214, v233, 1.0, s[8:9]
	v_cmp_gt_f32_e32 vcc, 1.0, v214
	s_waitcnt vmcnt(7)
	ds_write_b128 v204, v[98:101]
	s_waitcnt vmcnt(6)
	ds_write_b128 v205, v[138:141]
	s_cbranch_vccz .LBB0_606
	s_and_saveexec_b64 s[12:13], s[6:7]
	ds_write_b32 v189, v214 offset:128
	s_or_b64 exec, exec, s[12:13]
	s_waitcnt lgkmcnt(0)
	v_add_u32_e32 v232, v181, v180
	ds_read_b128 v[98:101], v232 offset:224
	ds_read_b128 v[138:141], v232 offset:192
	ds_read_b128 v[102:105], v232 offset:160
	ds_read_b128 v[142:145], v232 offset:128
	s_waitcnt lgkmcnt(3)
	v_pk_mul_f32 v[12:13], v[12:13], v[98:99]
	s_waitcnt lgkmcnt(2)
	v_pk_mul_f32 v[8:9], v[8:9], v[138:139]
	s_waitcnt lgkmcnt(1)
	v_pk_mul_f32 v[4:5], v[4:5], v[102:103]
	v_pk_mul_f32 v[14:15], v[14:15], v[100:101]
	v_pk_mul_f32 v[10:11], v[10:11], v[140:141]
	v_pk_mul_f32 v[6:7], v[6:7], v[104:105]
	s_waitcnt lgkmcnt(0)
	v_pk_mul_f32 v[2:3], v[2:3], v[144:145]
	v_pk_mul_f32 v[0:1], v[0:1], v[142:143]
	v_pk_mul_f32 v[60:61], v[60:61], v[98:99]
	v_pk_mul_f32 v[56:57], v[56:57], v[138:139]
	v_pk_mul_f32 v[52:53], v[52:53], v[102:103]
	v_pk_mul_f32 v[62:63], v[62:63], v[100:101]
	v_pk_mul_f32 v[58:59], v[58:59], v[140:141]
	v_pk_mul_f32 v[54:55], v[54:55], v[104:105]
	v_pk_mul_f32 v[50:51], v[50:51], v[144:145]
	v_pk_mul_f32 v[48:49], v[48:49], v[142:143]
	v_pk_mul_f32 v[44:45], v[44:45], v[98:99]
	v_pk_mul_f32 v[40:41], v[40:41], v[138:139]
	v_pk_mul_f32 v[36:37], v[36:37], v[102:103]
	v_pk_mul_f32 v[46:47], v[46:47], v[100:101]
	v_pk_mul_f32 v[42:43], v[42:43], v[140:141]
	v_pk_mul_f32 v[38:39], v[38:39], v[104:105]
	v_pk_mul_f32 v[34:35], v[34:35], v[144:145]
	v_pk_mul_f32 v[32:33], v[32:33], v[142:143]
	v_pk_mul_f32 v[28:29], v[28:29], v[98:99]
	v_pk_mul_f32 v[24:25], v[24:25], v[138:139]
	v_pk_mul_f32 v[20:21], v[20:21], v[102:103]
	v_pk_mul_f32 v[30:31], v[30:31], v[100:101]
	v_pk_mul_f32 v[26:27], v[26:27], v[140:141]
	v_pk_mul_f32 v[22:23], v[22:23], v[104:105]
	v_pk_mul_f32 v[18:19], v[18:19], v[144:145]
	v_pk_mul_f32 v[16:17], v[16:17], v[142:143]
; __device__ __forceinline__ void finishSM(f32x16& p0, f32x16& p1, float alpha, float& l_reg, bf16x8& pa0, bf16x8& pa1, bf16x8& pa2, bf16x8& pa3) {
;   for (int r = 0; r < 16; ++r) p1[r] = __builtin_amdgcn_exp2f(p1[r]);
;   float ps = 0; for (int r = 0; r < 16; ++r) ps += p0[r]; for (int r = 0; r < 16; ++r) ps += p1[r];
;   { auto rr = __builtin_amdgcn_permlane32_swap(__float_as_uint(ps), __float_as_uint(ps), false, false);
;     ps = __uint_as_float(rr[0]) + __uint_as_float(rr[1]); }
;   l_reg = l_reg * alpha + ps;
;     ...
;   PK4(p0, 0, pa0); PK4(p0, 8, pa1); PK4(p1, 0, pa2); PK4(p1, 8, pa3);
;     ...
; }
; __device__ __forceinline__ void qkt(f32x16& p0, f32x16& p1, const bf16* Ks, const bf16x8* qr, int r32, int hi) {
;   p0 = f32x16{}; p1 = f32x16{};
;   for (int d0 = 0; d0 < 8; ++d0) { int cb = (d0 * 16 + hi * 8) * 2;
;     bf16x8 b0 = *reinterpret_cast<const bf16x8*>((const char*)Ks + KSWZ(r32, cb));
;     bf16x8 b1 = *reinterpret_cast<const bf16x8*>((const char*)Ks + KSWZ(32 + r32, cb));
;     p0 = __builtin_amdgcn_mfma_f32_32x32x16_bf16(b0, qr[d0], p0, 0, 0, 0);
;     p1 = __builtin_amdgcn_mfma_f32_32x32x16_bf16(b1, qr[d0], p1, 0, 0, 0); }
; }
.LBB0_606:
	ds_read_b128 v[64:67], v192 offset:32768
	ds_read_b128 v[68:71], v192 offset:40960
	ds_read_b128 v[242:245], v201 offset:32768
	ds_read_b128 v[246:249], v201 offset:40960
	v_add_f32_e32 v230, 0, v162
	v_add_f32_e32 v230, v163, v230
	s_waitcnt lgkmcnt(3)
	v_mfma_f32_32x32x16_bf16 v[80:95], v[64:67], v[126:129], 0
	v_add_f32_e32 v230, v164, v230
	v_add_f32_e32 v230, v175, v230
	v_add_f32_e32 v230, v176, v230
	v_add_f32_e32 v230, v177, v230
	v_add_f32_e32 v230, v165, v230
	v_add_f32_e32 v230, v174, v230
	v_add_f32_e32 v230, v166, v230
	s_waitcnt lgkmcnt(2)
	v_mfma_f32_32x32x16_bf16 v[64:79], v[68:71], v[126:129], 0
	v_add_f32_e32 v230, v167, v230
	v_add_f32_e32 v230, v172, v230
	v_add_f32_e32 v230, v173, v230
	v_exp_f32_e32 v223, v223
	v_add_f32_e32 v230, v168, v230
	v_exp_f32_e32 v224, v224
	v_add_f32_e32 v230, v169, v230
	s_waitcnt lgkmcnt(1)
	v_mfma_f32_32x32x16_bf16 v[80:95], v[242:245], v[122:125], v[80:95]
	v_exp_f32_e32 v225, v225
	v_add_f32_e32 v230, v170, v230
	v_exp_f32_e32 v226, v226
	v_add_f32_e32 v230, v171, v230
	v_exp_f32_e32 v227, v227
	v_add_f32_e32 v230, v223, v230
	v_exp_f32_e32 v216, v216
	s_waitcnt lgkmcnt(0)
	v_mfma_f32_32x32x16_bf16 v[64:79], v[246:249], v[122:125], v[64:79]
	ds_read_b128 v[242:245], v200 offset:32768
	ds_read_b128 v[246:249], v200 offset:40960
	v_add_f32_e32 v230, v224, v230
	v_exp_f32_e32 v217, v217
	v_add_f32_e32 v230, v225, v230
	v_exp_f32_e32 v218, v218
	v_add_f32_e32 v230, v226, v230
	v_exp_f32_e32 v219, v219
	s_waitcnt lgkmcnt(1)
	v_mfma_f32_32x32x16_bf16 v[80:95], v[242:245], v[134:137], v[80:95]
	v_add_f32_e32 v230, v227, v230
	v_exp_f32_e32 v220, v220
	v_add_f32_e32 v230, v216, v230
	v_exp_f32_e32 v221, v221
	v_add_f32_e32 v230, v217, v230
	v_exp_f32_e32 v222, v222
	v_add_f32_e32 v230, v218, v230
	s_waitcnt lgkmcnt(0)
	v_mfma_f32_32x32x16_bf16 v[64:79], v[246:249], v[134:137], v[64:79]
	ds_read_b128 v[242:245], v195 offset:32768
	ds_read_b128 v[246:249], v195 offset:40960
	v_exp_f32_e32 v215, v215
	v_add_f32_e32 v230, v219, v230
	v_exp_f32_e32 v228, v228
	v_add_f32_e32 v230, v220, v230
	v_exp_f32_e32 v229, v229
	v_add_f32_e32 v230, v221, v230
	s_waitcnt lgkmcnt(1)
	v_mfma_f32_32x32x16_bf16 v[80:95], v[242:245], v[130:133], v[80:95]
	v_exp_f32_e32 v213, v213
	v_add_f32_e32 v230, v222, v230
	v_add_f32_e32 v230, v215, v230
	v_add_f32_e32 v230, v228, v230
	v_add_f32_e32 v230, v229, v230
	v_add_f32_e32 v231, v213, v230
	v_mov_b32_e32 v241, v231
	s_waitcnt lgkmcnt(0)
	v_mfma_f32_32x32x16_bf16 v[64:79], v[246:249], v[130:133], v[64:79]
	ds_read_b128 v[242:245], v194 offset:32768
	ds_read_b128 v[246:249], v194 offset:40960
	v_cvt_pk_bf16_f32 v162, v162, v163
	v_cvt_pk_bf16_f32 v163, v164, v175
	v_cvt_pk_bf16_f32 v164, v176, v177
	v_cvt_pk_bf16_f32 v165, v165, v174
	v_cvt_pk_bf16_f32 v166, v166, v167
	v_cvt_pk_bf16_f32 v167, v172, v173
	s_waitcnt lgkmcnt(1)
	v_mfma_f32_32x32x16_bf16 v[80:95], v[242:245], v[118:121], v[80:95]
	v_cvt_pk_bf16_f32 v168, v168, v169
	v_cvt_pk_bf16_f32 v169, v170, v171
	v_cvt_pk_bf16_f32 v170, v223, v224
	v_cvt_pk_bf16_f32 v171, v225, v226
	v_cvt_pk_bf16_f32 v172, v227, v216
	v_cvt_pk_bf16_f32 v173, v217, v218
	v_cvt_pk_bf16_f32 v174, v219, v220
	s_waitcnt lgkmcnt(0)
	v_mfma_f32_32x32x16_bf16 v[64:79], v[246:249], v[118:121], v[64:79]
	ds_read_b128 v[242:245], v193 offset:32768
	ds_read_b128 v[246:249], v193 offset:40960
	v_cvt_pk_bf16_f32 v175, v221, v222
	v_cvt_pk_bf16_f32 v176, v215, v228
	v_cvt_pk_bf16_f32 v177, v229, v213
	v_permlane32_swap_b32_e32 v231, v241
	v_permlane32_swap_b32_e32 v162, v164
	s_waitcnt lgkmcnt(1)
	v_mfma_f32_32x32x16_bf16 v[80:95], v[242:245], v[114:117], v[80:95]
	v_permlane32_swap_b32_e32 v163, v165
	v_permlane32_swap_b32_e32 v166, v168
	v_permlane32_swap_b32_e32 v167, v169
	v_permlane32_swap_b32_e32 v170, v172
	s_waitcnt lgkmcnt(0)
	v_mfma_f32_32x32x16_bf16 v[64:79], v[246:249], v[114:117], v[64:79]
	ds_read_b128 v[242:245], v207 offset:32768
	ds_read_b128 v[246:249], v207 offset:40960
	v_permlane32_swap_b32_e32 v171, v173
	v_permlane32_swap_b32_e32 v174, v176
	v_permlane32_swap_b32_e32 v175, v177
	s_waitcnt lgkmcnt(1)
	v_mfma_f32_32x32x16_bf16 v[80:95], v[242:245], v[110:113], v[80:95]
	s_waitcnt lgkmcnt(0)
	v_mfma_f32_32x32x16_bf16 v[64:79], v[246:249], v[110:113], v[64:79]
	ds_read_b128 v[242:245], v206 offset:32768
	ds_read_b128 v[246:249], v206 offset:40960
	s_waitcnt lgkmcnt(1)
	v_mfma_f32_32x32x16_bf16 v[80:95], v[242:245], v[106:109], v[80:95]
	s_waitcnt lgkmcnt(0)
	v_mfma_f32_32x32x16_bf16 v[64:79], v[246:249], v[106:109], v[64:79]
	s_cmp_ge_u32 s40, s41
	s_cselect_b64 s[12:13], -1, 0
	s_and_b64 vcc, exec, s[12:13]
	s_cbranch_vccnz .LBB0_608
	v_add_co_u32_e32 v98, vcc, 0xffff8000, v182
	s_nop 1
	v_addc_co_u32_e32 v99, vcc, -1, v183, vcc
	v_add_co_u32_e32 v102, vcc, 0xff6f8000, v182
	s_nop 1
	v_addc_co_u32_e32 v103, vcc, -1, v183, vcc
	v_add_co_u32_e32 v142, vcc, 0xff700000, v182
	global_load_dwordx4 v[98:101], v[98:99], off
	s_nop 0
	global_load_dwordx4 v[102:105], v[102:103], off
	v_addc_co_u32_e32 v143, vcc, -1, v183, vcc
	global_load_dwordx4 v[138:141], v[182:183], off
	s_nop 0
	global_load_dwordx4 v[142:145], v[142:143], off

; __device__ __forceinline__ void partialSM(f32x16& p0, f32x16& p1, float& m_reg, float& mn, float& alpha) {
;   constexpr float C = SCALE * 1.4426950408889634f;
;   float pmax = p0[0]; for (int r = 1; r < 16; ++r) pmax = fmaxf(pmax, p0[r]); for (int r = 0; r < 16; ++r) pmax = fmaxf(pmax, p1[r]);
;   { auto rr = __builtin_amdgcn_permlane32_swap(__float_as_uint(pmax), __float_as_uint(pmax), false, false);
;     pmax = fmaxf(__uint_as_float(rr[0]), __uint_as_float(rr[1])); }
;   if (__builtin_expect(__all(pmax - m_reg <= THR / SCALE), 1)) { mn = m_reg; alpha = 1.f; }
;   else { mn = fmaxf(m_reg, pmax); alpha = __builtin_amdgcn_exp2f((m_reg - mn) * C); m_reg = mn; }
;   float mnC = -mn * C;
;   for (int r = 0; r < 16; ++r) p0[r] = fmaf(p0[r], C, mnC); for (int r = 0; r < 16; ++r) p1[r] = fmaf(p1[r], C, mnC);
;   for (int r = 0; r < 16; ++r) p0[r] = __builtin_amdgcn_exp2f(p0[r]);
; }
; __device__ __forceinline__ void finishSM(f32x16& p0, f32x16& p1, float alpha, float& l_reg, bf16x8& pa0, bf16x8& pa1, bf16x8& pa2, bf16x8& pa3) {
;   for (int r = 0; r < 16; ++r) p1[r] = __builtin_amdgcn_exp2f(p1[r]);
;   float ps = 0; for (int r = 0; r < 16; ++r) ps += p0[r]; for (int r = 0; r < 16; ++r) ps += p1[r];
;   { auto rr = __builtin_amdgcn_permlane32_swap(__float_as_uint(ps), __float_as_uint(ps), false, false);
;     ps = __uint_as_float(rr[0]) + __uint_as_float(rr[1]); }
;   l_reg = l_reg * alpha + ps;
; template <int D0> __device__ __forceinline__ void pv_one(f32x16& od, int vb, bf16x8 pa0, bf16x8 pa1, bf16x8 pa2, bf16x8 pa3) {
;   const s16x4 l0 = tr_read<v_rd_off(D0, 0, 0)>(vb), h0 = tr_read<v_rd_off(D0, 0, 1)>(vb), l1 = tr_read<v_rd_off(D0, 1, 0)>(vb), h1 = tr_read<v_rd_off(D0, 1, 1)>(vb);
;   const s16x4 l2 = tr_read<v_rd_off(D0, 2, 0)>(vb), h2 = tr_read<v_rd_off(D0, 2, 1)>(vb), l3 = tr_read<v_rd_off(D0, 3, 0)>(vb), h3 = tr_read<v_rd_off(D0, 3, 1)>(vb);
;   asm volatile("s_waitcnt lgkmcnt(0)" ::: "memory"); SBAR();
;     ...
;   od = __builtin_amdgcn_mfma_f32_32x32x16_bf16(pa0, PK(l0, h0), od, 0, 0, 0);
;   od = __builtin_amdgcn_mfma_f32_32x32x16_bf16(pa1, PK(l1, h1), od, 0, 0, 0);
;   od = __builtin_amdgcn_mfma_f32_32x32x16_bf16(pa2, PK(l2, h2), od, 0, 0, 0);
;   od = __builtin_amdgcn_mfma_f32_32x32x16_bf16(pa3, PK(l3, h3), od, 0, 0, 0);
;     ...
; }
; __device__ __forceinline__ void pv_d0(f32x16* o, int vb, bf16x8 pa0, bf16x8 pa1, bf16x8 pa2, bf16x8 pa3) {
.Lk_wd:
	ds_write_b128 v202, v[154:157] offset:49152
	ds_write_b128 v203, v[158:161] offset:49152
	s_waitcnt lgkmcnt(2)
	s_nop 0
	v_mfma_f32_32x32x16_bf16 v[0:15], v[162:165], v[216:219], v[0:15]
	ds_read_b64_tr_b16 v[216:217], v191 offset:0x200
	ds_read_b64_tr_b16 v[218:219], v191 offset:0xa00
	v_max_f32_e32 v232, v81, v81
	v_max_f32_e32 v233, v80, v80
	v_max_f32_e32 v232, v233, v232
	v_max3_f32 v232, v232, v82, v83
	v_max3_f32 v232, v232, v84, v85
	v_max3_f32 v232, v232, v86, v87
	v_mfma_f32_32x32x16_bf16 v[0:15], v[166:169], v[220:223], v[0:15]
	ds_read_b64_tr_b16 v[220:221], v191 offset:0x1200
	ds_read_b64_tr_b16 v[222:223], v191 offset:0x1a00
	v_max3_f32 v232, v232, v88, v89
	v_max3_f32 v232, v232, v90, v91
	v_max3_f32 v232, v232, v92, v93
	v_max3_f32 v232, v232, v94, v95
	v_max3_f32 v232, v232, v64, v65
	v_max3_f32 v232, v232, v66, v67
	v_mfma_f32_32x32x16_bf16 v[0:15], v[170:173], v[224:227], v[0:15]
	ds_read_b64_tr_b16 v[224:225], v191 offset:0x2200
	ds_read_b64_tr_b16 v[226:227], v191 offset:0x2a00
	v_max3_f32 v232, v232, v68, v69
	v_max3_f32 v232, v232, v70, v71
	v_max3_f32 v232, v232, v72, v73
	v_max3_f32 v232, v232, v74, v75
	v_max3_f32 v232, v232, v76, v77
	v_max3_f32 v232, v232, v78, v79
	v_mfma_f32_32x32x16_bf16 v[0:15], v[174:177], v[242:245], v[0:15]
	ds_read_b64_tr_b16 v[242:243], v191 offset:0x3200
	ds_read_b64_tr_b16 v[244:245], v191 offset:0x3a00
	v_mov_b32_e32 v233, v232
	s_nop 1
	v_permlane32_swap_b32_e32 v232, v233
	v_max_f32_e32 v233, v233, v233
	v_max_f32_e32 v232, v232, v232
	v_max_f32_e32 v232, v232, v233
	s_waitcnt lgkmcnt(0)
	v_mfma_f32_32x32x16_bf16 v[48:63], v[162:165], v[216:219], v[48:63]
	ds_read_b64_tr_b16 v[216:217], v191 offset:0x400
	ds_read_b64_tr_b16 v[218:219], v191 offset:0xc00
	v_sub_f32_e32 v233, v232, v210
	v_cmp_ge_f32_e32 vcc, s68, v233
	v_max_f32_e32 v233, v210, v210
	v_max_f32_e32 v232, v233, v232
	v_sub_f32_e32 v233, v210, v232
	v_mul_f32_e32 v233, 0x3e0293ee, v233
	v_mfma_f32_32x32x16_bf16 v[48:63], v[166:169], v[220:223], v[48:63]
	ds_read_b64_tr_b16 v[220:221], v191 offset:0x1400
	ds_read_b64_tr_b16 v[222:223], v191 offset:0x1c00
	s_cmp_eq_u64 vcc, exec
	s_cselect_b64 s[8:9], -1, 0
	v_exp_f32_e32 v233, v233
	v_mfma_f32_32x32x16_bf16 v[48:63], v[170:173], v[224:227], v[48:63]
	ds_read_b64_tr_b16 v[224:225], v191 offset:0x2400
	ds_read_b64_tr_b16 v[226:227], v191 offset:0x2c00
	v_cndmask_b32_e64 v210, v232, v210, s[8:9]
	v_mul_f32_e32 v250, 0xbe0293ee, v210
	v_fmamk_f32 v80, v80, 0x3e0293ee, v250
	v_fmamk_f32 v81, v81, 0x3e0293ee, v250
	v_fmamk_f32 v82, v82, 0x3e0293ee, v250
	v_fmamk_f32 v83, v83, 0x3e0293ee, v250
	v_mfma_f32_32x32x16_bf16 v[48:63], v[174:177], v[242:245], v[48:63]
	ds_read_b64_tr_b16 v[242:243], v191 offset:0x3400
	ds_read_b64_tr_b16 v[244:245], v191 offset:0x3c00
	v_fmamk_f32 v84, v84, 0x3e0293ee, v250
	v_fmamk_f32 v85, v85, 0x3e0293ee, v250
	v_fmamk_f32 v86, v86, 0x3e0293ee, v250
	v_fmamk_f32 v87, v87, 0x3e0293ee, v250
	v_fmamk_f32 v88, v88, 0x3e0293ee, v250
	v_fmamk_f32 v89, v89, 0x3e0293ee, v250
	s_waitcnt lgkmcnt(0)
	v_mfma_f32_32x32x16_bf16 v[32:47], v[162:165], v[216:219], v[32:47]
	ds_read_b64_tr_b16 v[216:217], v191 offset:0x600
	ds_read_b64_tr_b16 v[218:219], v191 offset:0xe00
	v_fmamk_f32 v90, v90, 0x3e0293ee, v250
	v_fmamk_f32 v91, v91, 0x3e0293ee, v250
	v_fmamk_f32 v92, v92, 0x3e0293ee, v250
	v_fmamk_f32 v93, v93, 0x3e0293ee, v250
	v_fmamk_f32 v94, v94, 0x3e0293ee, v250
	v_fmamk_f32 v95, v95, 0x3e0293ee, v250
	v_mfma_f32_32x32x16_bf16 v[32:47], v[166:169], v[220:223], v[32:47]
	ds_read_b64_tr_b16 v[220:221], v191 offset:0x1600
	ds_read_b64_tr_b16 v[222:223], v191 offset:0x1e00
	v_exp_f32_e32 v80, v80
	v_exp_f32_e32 v81, v81
	v_exp_f32_e32 v82, v82
	v_mfma_f32_32x32x16_bf16 v[32:47], v[170:173], v[224:227], v[32:47]
	ds_read_b64_tr_b16 v[224:225], v191 offset:0x2600
	ds_read_b64_tr_b16 v[226:227], v191 offset:0x2e00
	v_exp_f32_e32 v83, v83
	v_exp_f32_e32 v84, v84
	v_exp_f32_e32 v85, v85
	v_mfma_f32_32x32x16_bf16 v[32:47], v[174:177], v[242:245], v[32:47]
	ds_read_b64_tr_b16 v[242:243], v191 offset:0x3600
	ds_read_b64_tr_b16 v[244:245], v191 offset:0x3e00
	v_exp_f32_e32 v86, v86
	v_exp_f32_e32 v87, v87
	v_exp_f32_e32 v88, v88
	s_waitcnt lgkmcnt(0)
	v_mfma_f32_32x32x16_bf16 v[16:31], v[162:165], v[216:219], v[16:31]
	v_exp_f32_e32 v89, v89
	v_exp_f32_e32 v90, v90
	v_exp_f32_e32 v91, v91
	v_mfma_f32_32x32x16_bf16 v[16:31], v[166:169], v[220:223], v[16:31]
	v_exp_f32_e32 v92, v92
	v_exp_f32_e32 v93, v93
	v_mfma_f32_32x32x16_bf16 v[16:31], v[170:173], v[224:227], v[16:31]
	v_exp_f32_e32 v94, v94
	v_exp_f32_e32 v95, v95
	v_mfma_f32_32x32x16_bf16 v[16:31], v[174:177], v[242:245], v[16:31]
	v_mov_b32_e32 v223, v80
	v_mov_b32_e32 v224, v81
	v_mov_b32_e32 v225, v82
	v_mov_b32_e32 v227, v83
	v_mov_b32_e32 v229, v84
	v_mov_b32_e32 v230, v85
	v_mov_b32_e32 v226, v86
	v_mov_b32_e32 v228, v87
	v_mov_b32_e32 v215, v88
	v_mov_b32_e32 v217, v89
	v_mov_b32_e32 v219, v90
	v_mov_b32_e32 v221, v91
	v_mov_b32_e32 v216, v92
	v_mov_b32_e32 v218, v93
	v_mov_b32_e32 v220, v94
	v_mov_b32_e32 v222, v95
	v_pk_fma_f32 v[176:177], v[64:65], s[84:85], v[250:251] op_sel_hi:[1,0,0]
	v_add_f32_e32 v64, v211, v212
	v_fmac_f32_e32 v64, v209, v190
	v_add_f32_e32 v190, v231, v241
	v_pk_fma_f32 v[174:175], v[66:67], s[84:85], v[250:251] op_sel_hi:[1,0,0]
	v_pk_fma_f32 v[170:171], v[68:69], s[84:85], v[250:251] op_sel_hi:[1,0,0]
	v_pk_fma_f32 v[166:167], v[70:71], s[84:85], v[250:251] op_sel_hi:[1,0,0]
	v_pk_fma_f32 v[164:165], v[72:73], s[84:85], v[250:251] op_sel_hi:[1,0,0]
	v_pk_fma_f32 v[172:173], v[74:75], s[84:85], v[250:251] op_sel_hi:[1,0,0]
	v_pk_fma_f32 v[168:169], v[76:77], s[84:85], v[250:251] op_sel_hi:[1,0,0]
	v_pk_fma_f32 v[162:163], v[78:79], s[84:85], v[250:251] op_sel_hi:[1,0,0]
	v_fmac_f32_e32 v190, v64, v214
	s_barrier
; #define SWAIT() do { if constexpr (SDEPTH == 2) asm volatile("s_waitcnt vmcnt(4)" ::: "memory"); else asm volatile("s_waitcnt vmcnt(0)" ::: "memory"); } while (0)
; #define RESC(a) do { if (__any((a) < 1.f)) { if (hi == 0) al_l[r32] = (a); asm volatile("s_waitcnt lgkmcnt(0)" ::: "memory"); \
;     for (int d = 0; d < 4; ++d) for (int r = 0; r < 16; ++r) o[d][r] *= al_l[crow(r, hi)]; } } while (0)
; __device__ __forceinline__ void attn_dense_body(const bf16* __restrict__ Qb, const bf16* __restrict__ Kh, const bf16* __restrict__ Vh,
;                                                 const unsigned short* __restrict__ Gb, unsigned short* __restrict__ Yb, int seq, char* lds, const int tid) {
;     ...
;     __syncthreads(); SWAIT(); SWRITE(1, SO);
;     RESC(alA); __syncthreads();
	s_waitcnt vmcnt(4)
	v_cndmask_b32_e64 v213, v233, 1.0, s[8:9]
	v_cmp_gt_f32_e32 vcc, 1.0, v213
	ds_write_b128 v204, v[146:149] offset:16384
	ds_write_b128 v205, v[150:153] offset:16384
	s_cbranch_vccz .LBB0_612
	s_and_saveexec_b64 s[18:19], s[6:7]
	ds_write_b32 v189, v213 offset:128
	s_or_b64 exec, exec, s[18:19]
	s_waitcnt lgkmcnt(0)
	v_add_u32_e32 v158, v181, v180
	ds_read_b128 v[146:149], v158 offset:224
	ds_read_b128 v[150:153], v158 offset:192
	ds_read_b128 v[154:157], v158 offset:160
	ds_read_b128 v[158:161], v158 offset:128
	s_waitcnt lgkmcnt(3)
	v_pk_mul_f32 v[12:13], v[12:13], v[146:147]
	s_waitcnt lgkmcnt(2)
	v_pk_mul_f32 v[8:9], v[8:9], v[150:151]
	s_waitcnt lgkmcnt(1)
	v_pk_mul_f32 v[4:5], v[4:5], v[154:155]
	v_pk_mul_f32 v[14:15], v[14:15], v[148:149]
	v_pk_mul_f32 v[10:11], v[10:11], v[152:153]
	v_pk_mul_f32 v[6:7], v[6:7], v[156:157]
	s_waitcnt lgkmcnt(0)
	v_pk_mul_f32 v[2:3], v[2:3], v[160:161]
	v_pk_mul_f32 v[0:1], v[0:1], v[158:159]
	v_pk_mul_f32 v[60:61], v[60:61], v[146:147]
	v_pk_mul_f32 v[56:57], v[56:57], v[150:151]
	v_pk_mul_f32 v[52:53], v[52:53], v[154:155]
	v_pk_mul_f32 v[62:63], v[62:63], v[148:149]
	v_pk_mul_f32 v[58:59], v[58:59], v[152:153]
	v_pk_mul_f32 v[54:55], v[54:55], v[156:157]
	v_pk_mul_f32 v[50:51], v[50:51], v[160:161]
	v_pk_mul_f32 v[48:49], v[48:49], v[158:159]
	v_pk_mul_f32 v[44:45], v[44:45], v[146:147]
	v_pk_mul_f32 v[40:41], v[40:41], v[150:151]
	v_pk_mul_f32 v[36:37], v[36:37], v[154:155]
	v_pk_mul_f32 v[46:47], v[46:47], v[148:149]
	v_pk_mul_f32 v[42:43], v[42:43], v[152:153]
	v_pk_mul_f32 v[38:39], v[38:39], v[156:157]
	v_pk_mul_f32 v[34:35], v[34:35], v[160:161]
	v_pk_mul_f32 v[32:33], v[32:33], v[158:159]
	v_pk_mul_f32 v[28:29], v[28:29], v[146:147]
	v_pk_mul_f32 v[24:25], v[24:25], v[150:151]
	v_pk_mul_f32 v[20:21], v[20:21], v[154:155]
	v_pk_mul_f32 v[30:31], v[30:31], v[148:149]
	v_pk_mul_f32 v[26:27], v[26:27], v[152:153]
	v_pk_mul_f32 v[22:23], v[22:23], v[156:157]
	v_pk_mul_f32 v[18:19], v[18:19], v[160:161]
	v_pk_mul_f32 v[16:17], v[16:17], v[158:159]
.LBB0_612:
	s_add_i32 s40, s40, 2
	v_lshl_add_u64 v[182:183], v[182:183], 0, s[82:83]
	s_and_b64 vcc, exec, s[12:13]
	s_cbranch_vccnz .LBB0_614
	v_mov_b32_e32 v209, v213
	s_branch .LBB0_602
